# speedup vs baseline: 1.0041x; 1.0041x over previous
.LBB0_349:
	s_or_b64 exec, exec, s[8:9]
	v_cvt_pk_bf16_f32 v246, v122, v123
	v_cvt_pk_bf16_f32 v247, v150, v151
	v_or_b32_e32 v121, 0x80, v142
	s_nop 1
	v_permlane16_swap_b32_e32 v244, v246
	v_permlane16_swap_b32_e32 v245, v247
	v_lshl_add_u64 v[242:243], v[124:125], 0, v[252:253]
	global_store_dwordx4 v[242:243], v[244:247], off
	v_pk_mul_f32 v[122:123], v[118:119], v[126:127]
	v_pk_mul_f32 v[118:119], v[116:117], v[148:149]
	v_mul_hi_i32 v116, v121, s74
	v_lshrrev_b32_e32 v117, 31, v116
	v_lshrrev_b32_e32 v116, 5, v116
	v_add_u32_e32 v116, v116, v117
	v_mul_lo_u32 v116, v116, s47
	v_sub_u32_e32 v116, v121, v116
	v_cmp_lt_i32_e64 s[8:9], s82, v116
	v_add_u32_e32 v116, 0xffffff80, v116
	v_lshrrev_b32_e32 v116, 1, v116
	s_and_saveexec_b64 s[10:11], s[8:9]
	s_cbranch_execz .LBB0_351
	v_mov_b32_e32 v117, v133
	v_lshl_add_u64 v[126:127], v[116:117], 3, v[146:147]
	global_load_dwordx4 v[158:161], v[126:127], off
	s_waitcnt vmcnt(0)
	v_pk_mul_f32 v[150:151], v[118:119], v[158:159] op_sel:[1,1] op_sel_hi:[0,1]
	v_mul_f32_e32 v162, v123, v161
	v_mul_f32_e32 v164, v122, v161
	v_pk_mul_f32 v[126:127], v[118:119], v[158:159]
	v_pk_fma_f32 v[118:119], v[118:119], v[158:159], v[150:151] op_sel_hi:[1,0,1]
	v_pk_fma_f32 v[158:159], v[122:123], v[160:161], v[162:163] op_sel_hi:[1,1,0] neg_lo:[0,0,1] neg_hi:[0,0,1]
	v_pk_fma_f32 v[160:161], v[122:123], v[160:161], v[164:165] op_sel:[1,0,0] op_sel_hi:[0,1,0]
	v_sub_f32_e32 v118, v126, v150
	v_mov_b32_e32 v122, v158
	v_mov_b32_e32 v123, v160

.LBB0_353:
	s_or_b64 exec, exec, s[36:37]
	v_cvt_pk_bf16_f32 v250, v114, v115
	v_cvt_pk_bf16_f32 v251, v118, v119
	v_or_b32_e32 v118, 16, v144
	v_ashrrev_i32_e32 v119, 31, v118
	s_nop 1
	v_permlane16_swap_b32_e32 v248, v250
	v_permlane16_swap_b32_e32 v249, v251
	v_lshl_add_u64 v[242:243], v[124:125], 0, v[252:253]
	global_store_dwordx4 v[242:243], v[248:251], off offset:256
	v_lshl_add_u64 v[114:115], v[118:119], 2, s[66:67]
	v_mov_b32_e32 v113, v234
	v_lshlrev_b64 v[124:125], 8, v[118:119]
	v_mul_f32_e32 v114, 0x3dd53b94, v113
	v_pk_mul_f32 v[122:123], v[110:111], v[114:115] op_sel_hi:[1,0]
	v_pk_mul_f32 v[110:111], v[108:109], v[114:115] op_sel_hi:[1,0]
	v_lshl_add_u64 v[108:109], s[16:17], 0, v[124:125]
	s_and_saveexec_b64 s[36:37], vcc
	s_cbranch_execz .LBB0_355
	v_lshl_add_u64 v[124:125], v[132:133], 3, v[108:109]
	global_load_dwordx4 v[124:127], v[124:125], off
	s_waitcnt vmcnt(0)
	v_pk_mul_f32 v[148:149], v[110:111], v[124:125] op_sel:[1,1] op_sel_hi:[0,1]
	v_mul_f32_e32 v150, v123, v127
	v_mul_f32_e32 v158, v122, v127
	v_pk_mul_f32 v[146:147], v[110:111], v[124:125]
	v_pk_fma_f32 v[110:111], v[110:111], v[124:125], v[148:149] op_sel_hi:[1,0,1]
	v_pk_fma_f32 v[124:125], v[122:123], v[126:127], v[150:151] op_sel_hi:[1,1,0] neg_lo:[0,0,1] neg_hi:[0,0,1]
	v_pk_fma_f32 v[126:127], v[122:123], v[126:127], v[158:159] op_sel:[1,0,0] op_sel_hi:[0,1,0]
	v_sub_f32_e32 v110, v146, v148
	v_mov_b32_e32 v122, v124
	v_mov_b32_e32 v123, v126

.LBB0_357:
	s_or_b64 exec, exec, s[36:37]
	v_pk_mul_f32 v[102:103], v[102:103], v[118:119]
	v_pk_mul_f32 v[100:101], v[100:101], v[114:115]
	v_cvt_pk_bf16_f32 v246, v104, v105
	v_cvt_pk_bf16_f32 v247, v106, v107
	s_nop 1
	v_permlane16_swap_b32_e32 v244, v246
	v_permlane16_swap_b32_e32 v245, v247
	v_lshl_add_u64 v[242:243], v[110:111], 0, v[252:253]
	global_store_dwordx4 v[242:243], v[244:247], off
	s_and_saveexec_b64 s[36:37], s[8:9]
	s_cbranch_execz .LBB0_359
	v_mov_b32_e32 v117, v133
	v_lshl_add_u64 v[104:105], v[116:117], 3, v[108:109]
	global_load_dwordx4 v[104:107], v[104:105], off
	s_waitcnt vmcnt(0)
	v_pk_mul_f32 v[122:123], v[100:101], v[104:105] op_sel:[1,1] op_sel_hi:[0,1]
	v_mul_f32_e32 v124, v103, v107
	v_mul_f32_e32 v126, v102, v107
	v_pk_mul_f32 v[118:119], v[100:101], v[104:105]
	v_pk_fma_f32 v[100:101], v[100:101], v[104:105], v[122:123] op_sel_hi:[1,0,1]
	v_pk_fma_f32 v[104:105], v[102:103], v[106:107], v[124:125] op_sel_hi:[1,1,0] neg_lo:[0,0,1] neg_hi:[0,0,1]
	v_pk_fma_f32 v[106:107], v[102:103], v[106:107], v[126:127] op_sel:[1,0,0] op_sel_hi:[0,1,0]
	v_sub_f32_e32 v100, v118, v122
	v_mov_b32_e32 v102, v104
	v_mov_b32_e32 v103, v106

.LBB0_361:
	s_or_b64 exec, exec, s[36:37]
	v_cvt_pk_bf16_f32 v250, v96, v97
	v_cvt_pk_bf16_f32 v251, v98, v99
	v_or_b32_e32 v98, 32, v144
	v_ashrrev_i32_e32 v99, 31, v98
	s_nop 1
	v_permlane16_swap_b32_e32 v248, v250
	v_permlane16_swap_b32_e32 v249, v251
	v_lshl_add_u64 v[242:243], v[110:111], 0, v[252:253]
	global_store_dwordx4 v[242:243], v[248:251], off offset:256
	v_lshl_add_u64 v[96:97], v[98:99], 2, s[66:67]
	v_mov_b32_e32 v96, v235
	v_lshlrev_b64 v[102:103], 8, v[98:99]
	v_mul_f32_e32 v96, 0x3dd53b94, v96
	v_pk_mul_f32 v[100:101], v[94:95], v[96:97] op_sel_hi:[1,0]
	v_pk_mul_f32 v[94:95], v[92:93], v[96:97] op_sel_hi:[1,0]
	v_lshl_add_u64 v[92:93], s[16:17], 0, v[102:103]
	s_and_saveexec_b64 s[36:37], vcc
	s_cbranch_execz .LBB0_363
	v_lshl_add_u64 v[102:103], v[132:133], 3, v[92:93]
	global_load_dwordx4 v[102:105], v[102:103], off
	s_waitcnt vmcnt(0)
	v_pk_mul_f32 v[108:109], v[94:95], v[102:103] op_sel:[1,1] op_sel_hi:[0,1]
	v_mul_f32_e32 v110, v101, v105
	v_mul_f32_e32 v114, v100, v105
	v_pk_mul_f32 v[106:107], v[94:95], v[102:103]
	v_pk_fma_f32 v[94:95], v[94:95], v[102:103], v[108:109] op_sel_hi:[1,0,1]
	v_pk_fma_f32 v[102:103], v[100:101], v[104:105], v[110:111] op_sel_hi:[1,1,0] neg_lo:[0,0,1] neg_hi:[0,0,1]
	v_pk_fma_f32 v[104:105], v[100:101], v[104:105], v[114:115] op_sel:[1,0,0] op_sel_hi:[0,1,0]
	v_sub_f32_e32 v94, v106, v108
	v_mov_b32_e32 v100, v102
	v_mov_b32_e32 v101, v104

.LBB0_365:
	s_or_b64 exec, exec, s[36:37]
	v_pk_mul_f32 v[86:87], v[86:87], v[98:99]
	v_pk_mul_f32 v[84:85], v[84:85], v[96:97]
	v_cvt_pk_bf16_f32 v246, v88, v89
	v_cvt_pk_bf16_f32 v247, v90, v91
	s_nop 1
	v_permlane16_swap_b32_e32 v244, v246
	v_permlane16_swap_b32_e32 v245, v247
	v_lshl_add_u64 v[242:243], v[94:95], 0, v[252:253]
	global_store_dwordx4 v[242:243], v[244:247], off
	s_and_saveexec_b64 s[36:37], s[8:9]
	s_cbranch_execz .LBB0_367
	v_mov_b32_e32 v117, v133
	v_lshl_add_u64 v[88:89], v[116:117], 3, v[92:93]
	global_load_dwordx4 v[88:91], v[88:89], off
	s_waitcnt vmcnt(0)
	v_pk_mul_f32 v[100:101], v[84:85], v[88:89] op_sel:[1,1] op_sel_hi:[0,1]
	v_mul_f32_e32 v102, v87, v91
	v_mul_f32_e32 v104, v86, v91
	v_pk_mul_f32 v[98:99], v[84:85], v[88:89]
	v_pk_fma_f32 v[84:85], v[84:85], v[88:89], v[100:101] op_sel_hi:[1,0,1]
	v_pk_fma_f32 v[88:89], v[86:87], v[90:91], v[102:103] op_sel_hi:[1,1,0] neg_lo:[0,0,1] neg_hi:[0,0,1]
	v_pk_fma_f32 v[90:91], v[86:87], v[90:91], v[104:105] op_sel:[1,0,0] op_sel_hi:[0,1,0]
	v_sub_f32_e32 v84, v98, v100
	v_mov_b32_e32 v86, v88
	v_mov_b32_e32 v87, v90

.LBB0_369:
	s_or_b64 exec, exec, s[36:37]
	v_cvt_pk_bf16_f32 v250, v80, v81
	v_cvt_pk_bf16_f32 v251, v82, v83
	v_or_b32_e32 v82, 48, v144
	v_ashrrev_i32_e32 v83, 31, v82
	s_nop 1
	v_permlane16_swap_b32_e32 v248, v250
	v_permlane16_swap_b32_e32 v249, v251
	v_lshl_add_u64 v[242:243], v[94:95], 0, v[252:253]
	global_store_dwordx4 v[242:243], v[248:251], off offset:256
	v_lshl_add_u64 v[80:81], v[82:83], 2, s[66:67]
	v_mov_b32_e32 v80, v236
	v_lshlrev_b64 v[86:87], 8, v[82:83]
	v_mul_f32_e32 v80, 0x3dd53b94, v80
	v_pk_mul_f32 v[84:85], v[78:79], v[80:81] op_sel_hi:[1,0]
	v_pk_mul_f32 v[78:79], v[76:77], v[80:81] op_sel_hi:[1,0]
	v_lshl_add_u64 v[76:77], s[16:17], 0, v[86:87]
	s_and_saveexec_b64 s[36:37], vcc
	s_cbranch_execz .LBB0_371
	v_lshl_add_u64 v[86:87], v[132:133], 3, v[76:77]
	global_load_dwordx4 v[86:89], v[86:87], off
	s_waitcnt vmcnt(0)
	v_pk_mul_f32 v[92:93], v[78:79], v[86:87] op_sel:[1,1] op_sel_hi:[0,1]
	v_mul_f32_e32 v94, v85, v89
	v_mul_f32_e32 v96, v84, v89
	v_pk_mul_f32 v[90:91], v[78:79], v[86:87]
	v_pk_fma_f32 v[78:79], v[78:79], v[86:87], v[92:93] op_sel_hi:[1,0,1]
	v_pk_fma_f32 v[86:87], v[84:85], v[88:89], v[94:95] op_sel_hi:[1,1,0] neg_lo:[0,0,1] neg_hi:[0,0,1]
	v_pk_fma_f32 v[88:89], v[84:85], v[88:89], v[96:97] op_sel:[1,0,0] op_sel_hi:[0,1,0]
	v_sub_f32_e32 v78, v90, v92
	v_mov_b32_e32 v84, v86
	v_mov_b32_e32 v85, v88

.LBB0_373:
	s_or_b64 exec, exec, s[36:37]
	v_pk_mul_f32 v[70:71], v[70:71], v[82:83]
	v_pk_mul_f32 v[68:69], v[68:69], v[80:81]
	v_cvt_pk_bf16_f32 v246, v72, v73
	v_cvt_pk_bf16_f32 v247, v74, v75
	s_nop 1
	v_permlane16_swap_b32_e32 v244, v246
	v_permlane16_swap_b32_e32 v245, v247
	v_lshl_add_u64 v[242:243], v[78:79], 0, v[252:253]
	global_store_dwordx4 v[242:243], v[244:247], off
	s_and_saveexec_b64 s[36:37], s[8:9]
	s_cbranch_execz .LBB0_375
	v_mov_b32_e32 v117, v133
	v_lshl_add_u64 v[72:73], v[116:117], 3, v[76:77]
	global_load_dwordx4 v[72:75], v[72:73], off
	s_waitcnt vmcnt(0)
	v_pk_mul_f32 v[84:85], v[68:69], v[72:73] op_sel:[1,1] op_sel_hi:[0,1]
	v_mul_f32_e32 v86, v71, v75
	v_mul_f32_e32 v88, v70, v75
	v_pk_mul_f32 v[82:83], v[68:69], v[72:73]
	v_pk_fma_f32 v[68:69], v[68:69], v[72:73], v[84:85] op_sel_hi:[1,0,1]
	v_pk_fma_f32 v[72:73], v[70:71], v[74:75], v[86:87] op_sel_hi:[1,1,0] neg_lo:[0,0,1] neg_hi:[0,0,1]
	v_pk_fma_f32 v[74:75], v[70:71], v[74:75], v[88:89] op_sel:[1,0,0] op_sel_hi:[0,1,0]
	v_sub_f32_e32 v68, v82, v84
	v_mov_b32_e32 v70, v72
	v_mov_b32_e32 v71, v74

.LBB0_377:
	s_or_b64 exec, exec, s[36:37]
	v_cvt_pk_bf16_f32 v250, v64, v65
	v_cvt_pk_bf16_f32 v251, v66, v67
	v_add_u32_e32 v66, 0x80, v144
	v_ashrrev_i32_e32 v67, 31, v66
	s_nop 1
	v_permlane16_swap_b32_e32 v248, v250
	v_permlane16_swap_b32_e32 v249, v251
	v_lshl_add_u64 v[242:243], v[78:79], 0, v[252:253]
	global_store_dwordx4 v[242:243], v[248:251], off offset:256
	v_lshl_add_u64 v[64:65], v[66:67], 2, s[66:67]
	v_mov_b32_e32 v64, v237
	v_lshlrev_b64 v[70:71], 8, v[66:67]
	v_mul_f32_e32 v64, 0x3dd53b94, v64
	v_pk_mul_f32 v[68:69], v[62:63], v[64:65] op_sel_hi:[1,0]
	v_pk_mul_f32 v[62:63], v[60:61], v[64:65] op_sel_hi:[1,0]
	v_lshl_add_u64 v[60:61], s[16:17], 0, v[70:71]
	s_and_saveexec_b64 s[36:37], vcc
	s_cbranch_execz .LBB0_379
	v_lshl_add_u64 v[70:71], v[132:133], 3, v[60:61]
	global_load_dwordx4 v[70:73], v[70:71], off
	s_waitcnt vmcnt(0)
	v_pk_mul_f32 v[76:77], v[62:63], v[70:71] op_sel:[1,1] op_sel_hi:[0,1]
	v_mul_f32_e32 v78, v69, v73
	v_mul_f32_e32 v80, v68, v73
	v_pk_mul_f32 v[74:75], v[62:63], v[70:71]
	v_pk_fma_f32 v[62:63], v[62:63], v[70:71], v[76:77] op_sel_hi:[1,0,1]
	v_pk_fma_f32 v[70:71], v[68:69], v[72:73], v[78:79] op_sel_hi:[1,1,0] neg_lo:[0,0,1] neg_hi:[0,0,1]
	v_pk_fma_f32 v[72:73], v[68:69], v[72:73], v[80:81] op_sel:[1,0,0] op_sel_hi:[0,1,0]
	v_sub_f32_e32 v62, v74, v76
	v_mov_b32_e32 v68, v70
	v_mov_b32_e32 v69, v72

.LBB0_381:
	s_or_b64 exec, exec, s[36:37]
	v_pk_mul_f32 v[54:55], v[54:55], v[66:67]
	v_pk_mul_f32 v[52:53], v[52:53], v[64:65]
	v_cvt_pk_bf16_f32 v246, v56, v57
	v_cvt_pk_bf16_f32 v247, v58, v59
	s_nop 1
	v_permlane16_swap_b32_e32 v244, v246
	v_permlane16_swap_b32_e32 v245, v247
	v_lshl_add_u64 v[242:243], v[62:63], 0, v[252:253]
	global_store_dwordx4 v[242:243], v[244:247], off
	s_and_saveexec_b64 s[36:37], s[8:9]
	s_cbranch_execz .LBB0_383
	v_mov_b32_e32 v117, v133
	v_lshl_add_u64 v[56:57], v[116:117], 3, v[60:61]
	global_load_dwordx4 v[56:59], v[56:57], off
	s_waitcnt vmcnt(0)
	v_pk_mul_f32 v[68:69], v[52:53], v[56:57] op_sel:[1,1] op_sel_hi:[0,1]
	v_mul_f32_e32 v70, v55, v59
	v_mul_f32_e32 v72, v54, v59
	v_pk_mul_f32 v[66:67], v[52:53], v[56:57]
	v_pk_fma_f32 v[52:53], v[52:53], v[56:57], v[68:69] op_sel_hi:[1,0,1]
	v_pk_fma_f32 v[56:57], v[54:55], v[58:59], v[70:71] op_sel_hi:[1,1,0] neg_lo:[0,0,1] neg_hi:[0,0,1]
	v_pk_fma_f32 v[58:59], v[54:55], v[58:59], v[72:73] op_sel:[1,0,0] op_sel_hi:[0,1,0]
	v_sub_f32_e32 v52, v66, v68
	v_mov_b32_e32 v54, v56
	v_mov_b32_e32 v55, v58

.LBB0_385:
	s_or_b64 exec, exec, s[36:37]
	v_cvt_pk_bf16_f32 v250, v48, v49
	v_cvt_pk_bf16_f32 v251, v50, v51
	v_add_u32_e32 v50, 0x90, v144
	v_ashrrev_i32_e32 v51, 31, v50
	s_nop 1
	v_permlane16_swap_b32_e32 v248, v250
	v_permlane16_swap_b32_e32 v249, v251
	v_lshl_add_u64 v[242:243], v[62:63], 0, v[252:253]
	global_store_dwordx4 v[242:243], v[248:251], off offset:256
	v_lshl_add_u64 v[48:49], v[50:51], 2, s[66:67]
	v_mov_b32_e32 v48, v238
	v_lshlrev_b64 v[54:55], 8, v[50:51]
	v_mul_f32_e32 v48, 0x3dd53b94, v48
	v_pk_mul_f32 v[52:53], v[46:47], v[48:49] op_sel_hi:[1,0]
	v_pk_mul_f32 v[46:47], v[44:45], v[48:49] op_sel_hi:[1,0]
	v_lshl_add_u64 v[44:45], s[16:17], 0, v[54:55]
	s_and_saveexec_b64 s[36:37], vcc
	s_cbranch_execz .LBB0_387
	v_lshl_add_u64 v[54:55], v[132:133], 3, v[44:45]
	global_load_dwordx4 v[54:57], v[54:55], off
	s_waitcnt vmcnt(0)
	v_pk_mul_f32 v[60:61], v[46:47], v[54:55] op_sel:[1,1] op_sel_hi:[0,1]
	v_mul_f32_e32 v62, v53, v57
	v_mul_f32_e32 v64, v52, v57
	v_pk_mul_f32 v[58:59], v[46:47], v[54:55]
	v_pk_fma_f32 v[46:47], v[46:47], v[54:55], v[60:61] op_sel_hi:[1,0,1]
	v_pk_fma_f32 v[54:55], v[52:53], v[56:57], v[62:63] op_sel_hi:[1,1,0] neg_lo:[0,0,1] neg_hi:[0,0,1]
	v_pk_fma_f32 v[56:57], v[52:53], v[56:57], v[64:65] op_sel:[1,0,0] op_sel_hi:[0,1,0]
	v_sub_f32_e32 v46, v58, v60
	v_mov_b32_e32 v52, v54
	v_mov_b32_e32 v53, v56

.LBB0_389:
	s_or_b64 exec, exec, s[36:37]
	v_pk_mul_f32 v[38:39], v[38:39], v[50:51]
	v_pk_mul_f32 v[36:37], v[36:37], v[48:49]
	v_cvt_pk_bf16_f32 v246, v40, v41
	v_cvt_pk_bf16_f32 v247, v42, v43
	s_nop 1
	v_permlane16_swap_b32_e32 v244, v246
	v_permlane16_swap_b32_e32 v245, v247
	v_lshl_add_u64 v[242:243], v[46:47], 0, v[252:253]
	global_store_dwordx4 v[242:243], v[244:247], off
	s_and_saveexec_b64 s[36:37], s[8:9]
	s_cbranch_execz .LBB0_391
	v_mov_b32_e32 v117, v133
	v_lshl_add_u64 v[40:41], v[116:117], 3, v[44:45]
	global_load_dwordx4 v[40:43], v[40:41], off
	s_waitcnt vmcnt(0)
	v_pk_mul_f32 v[52:53], v[36:37], v[40:41] op_sel:[1,1] op_sel_hi:[0,1]
	v_mul_f32_e32 v54, v39, v43
	v_mul_f32_e32 v56, v38, v43
	v_pk_mul_f32 v[50:51], v[36:37], v[40:41]
	v_pk_fma_f32 v[36:37], v[36:37], v[40:41], v[52:53] op_sel_hi:[1,0,1]
	v_pk_fma_f32 v[40:41], v[38:39], v[42:43], v[54:55] op_sel_hi:[1,1,0] neg_lo:[0,0,1] neg_hi:[0,0,1]
	v_pk_fma_f32 v[42:43], v[38:39], v[42:43], v[56:57] op_sel:[1,0,0] op_sel_hi:[0,1,0]
	v_sub_f32_e32 v36, v50, v52
	v_mov_b32_e32 v38, v40
	v_mov_b32_e32 v39, v42

.LBB0_393:
	s_or_b64 exec, exec, s[36:37]
	v_cvt_pk_bf16_f32 v250, v32, v33
	v_cvt_pk_bf16_f32 v251, v34, v35
	v_add_u32_e32 v34, 0xa0, v144
	v_ashrrev_i32_e32 v35, 31, v34
	s_nop 1
	v_permlane16_swap_b32_e32 v248, v250
	v_permlane16_swap_b32_e32 v249, v251
	v_lshl_add_u64 v[242:243], v[46:47], 0, v[252:253]
	global_store_dwordx4 v[242:243], v[248:251], off offset:256
	v_lshl_add_u64 v[32:33], v[34:35], 2, s[66:67]
	v_mov_b32_e32 v32, v239
	v_lshlrev_b64 v[38:39], 8, v[34:35]
	v_mul_f32_e32 v32, 0x3dd53b94, v32
	v_pk_mul_f32 v[36:37], v[30:31], v[32:33] op_sel_hi:[1,0]
	v_pk_mul_f32 v[30:31], v[28:29], v[32:33] op_sel_hi:[1,0]
	v_lshl_add_u64 v[28:29], s[16:17], 0, v[38:39]
	s_and_saveexec_b64 s[36:37], vcc
	s_cbranch_execz .LBB0_395
	v_lshl_add_u64 v[38:39], v[132:133], 3, v[28:29]
	global_load_dwordx4 v[38:41], v[38:39], off
	s_waitcnt vmcnt(0)
	v_pk_mul_f32 v[44:45], v[30:31], v[38:39] op_sel:[1,1] op_sel_hi:[0,1]
	v_mul_f32_e32 v46, v37, v41
	v_mul_f32_e32 v48, v36, v41
	v_pk_mul_f32 v[42:43], v[30:31], v[38:39]
	v_pk_fma_f32 v[30:31], v[30:31], v[38:39], v[44:45] op_sel_hi:[1,0,1]
	v_pk_fma_f32 v[38:39], v[36:37], v[40:41], v[46:47] op_sel_hi:[1,1,0] neg_lo:[0,0,1] neg_hi:[0,0,1]
	v_pk_fma_f32 v[40:41], v[36:37], v[40:41], v[48:49] op_sel:[1,0,0] op_sel_hi:[0,1,0]
	v_sub_f32_e32 v30, v42, v44
	v_mov_b32_e32 v36, v38
	v_mov_b32_e32 v37, v40

.LBB0_397:
	s_or_b64 exec, exec, s[36:37]
	v_pk_mul_f32 v[22:23], v[22:23], v[34:35]
	v_pk_mul_f32 v[20:21], v[20:21], v[32:33]
	v_cvt_pk_bf16_f32 v246, v24, v25
	v_cvt_pk_bf16_f32 v247, v26, v27
	s_nop 1
	v_permlane16_swap_b32_e32 v244, v246
	v_permlane16_swap_b32_e32 v245, v247
	v_lshl_add_u64 v[242:243], v[30:31], 0, v[252:253]
	global_store_dwordx4 v[242:243], v[244:247], off
	s_and_saveexec_b64 s[36:37], s[8:9]
	s_cbranch_execz .LBB0_399
	v_mov_b32_e32 v117, v133
	v_lshl_add_u64 v[24:25], v[116:117], 3, v[28:29]
	global_load_dwordx4 v[24:27], v[24:25], off
	s_waitcnt vmcnt(0)
	v_pk_mul_f32 v[36:37], v[20:21], v[24:25] op_sel:[1,1] op_sel_hi:[0,1]
	v_mul_f32_e32 v38, v23, v27
	v_mul_f32_e32 v40, v22, v27
	v_pk_mul_f32 v[34:35], v[20:21], v[24:25]
	v_pk_fma_f32 v[20:21], v[20:21], v[24:25], v[36:37] op_sel_hi:[1,0,1]
	v_pk_fma_f32 v[24:25], v[22:23], v[26:27], v[38:39] op_sel_hi:[1,1,0] neg_lo:[0,0,1] neg_hi:[0,0,1]
	v_pk_fma_f32 v[26:27], v[22:23], v[26:27], v[40:41] op_sel:[1,0,0] op_sel_hi:[0,1,0]
	v_sub_f32_e32 v20, v34, v36
	v_mov_b32_e32 v22, v24
	v_mov_b32_e32 v23, v26

.LBB0_401:
	s_or_b64 exec, exec, s[36:37]
	v_cvt_pk_bf16_f32 v250, v16, v17
	v_cvt_pk_bf16_f32 v251, v18, v19
	v_add_u32_e32 v18, 0xb0, v144
	v_ashrrev_i32_e32 v19, 31, v18
	s_nop 1
	v_permlane16_swap_b32_e32 v248, v250
	v_permlane16_swap_b32_e32 v249, v251
	v_lshl_add_u64 v[242:243], v[30:31], 0, v[252:253]
	global_store_dwordx4 v[242:243], v[248:251], off offset:256
	v_lshl_add_u64 v[16:17], v[18:19], 2, s[66:67]
	v_mov_b32_e32 v16, v240
	v_lshlrev_b64 v[22:23], 8, v[18:19]
	v_mul_f32_e32 v16, 0x3dd53b94, v16
	v_pk_mul_f32 v[20:21], v[14:15], v[16:17] op_sel_hi:[1,0]
	v_pk_mul_f32 v[14:15], v[12:13], v[16:17] op_sel_hi:[1,0]
	v_lshl_add_u64 v[12:13], s[16:17], 0, v[22:23]
	s_and_saveexec_b64 s[36:37], vcc
	s_cbranch_execz .LBB0_403
	v_lshl_add_u64 v[22:23], v[132:133], 3, v[12:13]
	global_load_dwordx4 v[22:25], v[22:23], off
	s_waitcnt vmcnt(0)
	v_pk_mul_f32 v[28:29], v[14:15], v[22:23] op_sel:[1,1] op_sel_hi:[0,1]
	v_mul_f32_e32 v30, v21, v25
	v_mul_f32_e32 v32, v20, v25
	v_pk_mul_f32 v[26:27], v[14:15], v[22:23]
	v_pk_fma_f32 v[14:15], v[14:15], v[22:23], v[28:29] op_sel_hi:[1,0,1]
	v_pk_fma_f32 v[22:23], v[20:21], v[24:25], v[30:31] op_sel_hi:[1,1,0] neg_lo:[0,0,1] neg_hi:[0,0,1]
	v_pk_fma_f32 v[24:25], v[20:21], v[24:25], v[32:33] op_sel:[1,0,0] op_sel_hi:[0,1,0]
	v_sub_f32_e32 v14, v26, v28
	v_mov_b32_e32 v20, v22
	v_mov_b32_e32 v21, v24

.LBB0_405:
	s_or_b64 exec, exec, s[36:37]
	v_pk_mul_f32 v[6:7], v[6:7], v[18:19]
	v_pk_mul_f32 v[4:5], v[4:5], v[16:17]
	v_cvt_pk_bf16_f32 v246, v8, v9
	v_cvt_pk_bf16_f32 v247, v10, v11
	s_nop 1
	v_permlane16_swap_b32_e32 v244, v246
	v_permlane16_swap_b32_e32 v245, v247
	v_lshl_add_u64 v[242:243], v[14:15], 0, v[252:253]
	global_store_dwordx4 v[242:243], v[244:247], off
	s_and_saveexec_b64 s[6:7], s[8:9]
	s_cbranch_execz .LBB0_407
	v_mov_b32_e32 v117, v133
	v_lshl_add_u64 v[8:9], v[116:117], 3, v[12:13]
	global_load_dwordx4 v[8:11], v[8:9], off
	s_waitcnt vmcnt(0)
	v_pk_mul_f32 v[20:21], v[4:5], v[8:9] op_sel:[1,1] op_sel_hi:[0,1]
	v_mul_f32_e32 v22, v7, v11
	v_mul_f32_e32 v24, v6, v11
	v_pk_mul_f32 v[18:19], v[4:5], v[8:9]
	v_pk_fma_f32 v[4:5], v[4:5], v[8:9], v[20:21] op_sel_hi:[1,0,1]
	v_pk_fma_f32 v[8:9], v[6:7], v[10:11], v[22:23] op_sel_hi:[1,1,0] neg_lo:[0,0,1] neg_hi:[0,0,1]
	v_pk_fma_f32 v[10:11], v[6:7], v[10:11], v[24:25] op_sel:[1,0,0] op_sel_hi:[0,1,0]
	v_sub_f32_e32 v4, v18, v20
	v_mov_b32_e32 v6, v8
	v_mov_b32_e32 v7, v10

.LBB0_409:
	s_or_b64 exec, exec, s[6:7]
	s_andn2_b64 vcc, exec, s[4:5]
	s_mov_b64 s[4:5], -1
	v_cvt_pk_bf16_f32 v250, v0, v1
	v_cvt_pk_bf16_f32 v251, v2, v3
	s_nop 1
	v_permlane16_swap_b32_e32 v248, v250
	v_permlane16_swap_b32_e32 v249, v251
	v_lshl_add_u64 v[242:243], v[14:15], 0, v[252:253]
	global_store_dwordx4 v[242:243], v[248:251], off offset:256
	s_cbranch_vccnz .LBB0_338
	s_andn2_b64 vcc, exec, s[18:19]
	s_cbranch_vccnz .LBB0_337
	s_barrier
	s_branch .LBB0_337
